# ssd_out head loop: next-head conv weights and D-skip scalar prefetched during MFMA section (no load-then-wait at point of use)
# speedup vs baseline: 1.0355x; 1.0040x over previous
.LBB0_371:
	s_or_b64 exec, exec, s[6:7]
	s_lshl_b32 s0, s0, 11
	s_lshl_b32 s1, s1, 6
	s_or_b32 s0, s1, s0
	s_or_b32 s6, s0, s20
	s_ashr_i32 s7, s6, 31
	v_ashrrev_i32_e32 v22, 3, v37
	s_lshl_b64 s[6:7], s[6:7], 14
	v_ashrrev_i32_e32 v23, 31, v22
	s_add_u32 s6, s26, s6
	s_addc_u32 s7, s27, s7
	v_lshlrev_b64 v[62:63], 8, v[22:23]
	v_lshlrev_b32_e32 v2, 5, v37
	v_lshl_add_u64 v[0:1], s[6:7], 0, v[62:63]
	v_and_b32_e32 v64, 0xe0, v2
	v_mov_b32_e32 v65, v173
	s_add_i32 s15, s15, s75
	v_lshl_add_u64 v[4:5], v[0:1], 0, v[64:65]
	v_or_b32_e32 v2, s15, v60
	v_mov_b64_e32 v[0:1], s[82:83]
	v_mad_i64_i32 v[66:67], s[6:7], v2, s37, v[0:1]
	s_lshl_b32 s30, s2, 1
	v_lshrrev_b32_e32 v21, 4, v39
	v_lshl_add_u64 v[0:1], v[66:67], 0, s[30:31]
	v_lshlrev_b32_e32 v26, 3, v21
	v_mov_b32_e32 v27, v173
	v_lshl_add_u64 v[0:1], v[0:1], 0, v[26:27]
	global_load_dwordx2 v[78:79], v[0:1], off
	global_load_dwordx2 v[76:77], v[0:1], off offset:32
	global_load_dwordx2 v[74:75], v[0:1], off offset:64
	global_load_dwordx2 v[72:73], v[0:1], off offset:96
	s_nop 0
	global_load_dwordx4 v[0:3], v[4:5], off offset:16
	s_nop 0
	global_load_dwordx4 v[4:7], v[4:5], off
	v_lshl_add_u32 v23, v10, 1, 0
	v_mad_i64_i32 v[34:35], s[6:7], v10, s37, 0
	v_mov_b32_e32 v10, 0x2200
	s_mul_i32 s2, s11, 0x1100
	v_mad_i64_i32 v[42:43], s[6:7], v15, s37, 0
	v_mad_u32_u24 v10, v60, s89, v10
	v_mov_b32_e32 v15, s2
	v_mov_b32_e32 v9, v173
	v_lshl_add_u32 v91, v36, 2, 0
	v_lshlrev_b32_e32 v61, 1, v36
	v_mad_i64_i32 v[28:29], s[6:7], v12, s37, 0
	v_mad_i64_i32 v[30:31], s[6:7], v13, s37, 0
	v_mad_i64_i32 v[32:33], s[6:7], v14, s37, 0
	v_mad_i64_i32 v[44:45], s[6:7], v16, s37, 0
	v_mad_i64_i32 v[46:47], s[6:7], v17, s37, 0
	v_mad_i64_i32 v[48:49], s[6:7], v18, s37, 0
	v_mad_i64_i32 v[50:51], s[6:7], v19, s37, 0
	v_mad_i64_i32 v[52:53], s[6:7], v20, s37, 0
	v_and_b32_e32 v13, 48, v39
	v_add_u32_e32 v97, v38, v10
	v_mad_u32_u24 v10, v60, s89, v15
	v_readlane_b32 s2, v255, 21
	v_mov_b32_e32 v12, 0x3300
	v_lshl_add_u64 v[58:59], s[4:5], 0, v[8:9]
	v_sub_u32_e32 v8, v91, v61
	v_mul_u32_u24_e32 v9, 0x440, v21
	v_add3_u32 v102, v10, v13, s2
	s_ashr_i32 s6, s11, 1
	s_or_b32 s2, s20, 1
	v_lshlrev_b32_e32 v56, 2, v11
	v_mov_b32_e32 v57, v173
	v_mul_u32_u24_e32 v11, 0x110, v11
	v_mad_u32_u24 v12, v60, s89, v12
	v_readlane_b32 s1, v255, 22
	v_mul_lo_u32 v14, v22, s89
	v_add_u32_e32 v101, v8, v9
	v_lshl_add_u64 v[8:9], s[26:27], 0, v[62:63]
	s_cmp_gt_i32 s6, -1
	v_mov_b32_e32 v37, v36
	v_add3_u32 v94, v41, v54, s1
	s_mov_b32 s1, 0
	v_lshl_add_u64 v[54:55], s[56:57], 0, v[56:57]
	v_lshl_add_u64 v[56:57], s[58:59], 0, v[56:57]
	v_lshl_add_u32 v95, v21, 5, 0
	v_add_u32_e32 v96, v23, v11
	v_add_u32_e32 v98, v38, v12
	v_add3_u32 v100, 0, v14, v64
	v_lshl_add_u64 v[60:61], v[8:9], 0, v[64:65]
	s_cselect_b64 s[44:45], -1, 0
	s_add_i32 s6, s6, 1
	v_lshl_add_u64 v[62:63], v[66:67], 0, v[26:27]
	s_waitcnt vmcnt(5)
	v_mov_b64_e32 v[64:65], v[78:79]
	s_waitcnt vmcnt(4)
	v_mov_b64_e32 v[66:67], v[76:77]
	s_waitcnt vmcnt(3)
	v_mov_b64_e32 v[68:69], v[74:75]
	s_waitcnt vmcnt(2)
	v_mov_b64_e32 v[70:71], v[72:73]
	s_lshl_b32 s4, s20, 8
	s_mov_b32 s5, 0
	v_lshl_add_u64 v[138:139], v[54:55], 0, s[4:5]
	v_lshl_add_u64 v[140:141], v[56:57], 0, s[4:5]
	global_load_dwordx2 v[128:129], v[138:139], off
	global_load_dwordx2 v[130:131], v[140:141], off
	s_mov_b64 s[4:5], 0x6000
	v_lshl_add_u64 v[140:141], v[138:139], 0, s[4:5]
	global_load_dwordx2 v[132:133], v[140:141], off
	s_mov_b64 s[4:5], 0xc000
	v_lshl_add_u64 v[140:141], v[138:139], 0, s[4:5]
	global_load_dwordx2 v[134:135], v[140:141], off
	s_mov_b64 s[4:5], 0x12000
	v_lshl_add_u64 v[140:141], v[138:139], 0, s[4:5]
	global_load_dwordx2 v[136:137], v[140:141], off
	s_waitcnt vmcnt(0)
.LBB0_372:
	s_or_b32 s46, s1, s20
	s_lshl_b32 s30, s46, 6
	s_lshl_b64 s[4:5], s[30:31], 2
	v_lshlrev_b32_e32 v23, 16, v83
	v_lshlrev_b32_e32 v22, 16, v84
	v_lshlrev_b32_e32 v81, 16, v85
	v_lshlrev_b32_e32 v80, 16, v86
	v_lshlrev_b32_e32 v105, 16, v87
	v_lshlrev_b32_e32 v104, 16, v88
	v_lshlrev_b32_e32 v107, 16, v89
	v_lshlrev_b32_e32 v106, 16, v90
	v_lshlrev_b32_e32 v108, 16, v89
	v_pk_mov_b32 v[114:115], v[80:81], v[104:105] op_sel:[1,0]
	v_pk_mov_b32 v[116:117], v[22:23], v[80:81] op_sel:[1,0]
	v_pk_mov_b32 v[118:119], v[104:105], v[106:107] op_sel:[1,0]
	v_lshlrev_b32_e32 v109, 16, v93
	v_lshlrev_b32_e32 v110, 16, v93
	v_mov_b32_e32 v120, v106
	v_mov_b32_e32 v121, v108
	v_lshlrev_b32_e32 v111, 16, v92
	v_mov_b32_e32 v122, v108
	v_mov_b32_e32 v123, v110
	v_lshlrev_b32_e32 v113, 16, v99
	v_lshlrev_b32_e32 v112, 16, v92
	v_and_b32_e32 v19, 0xffff0000, v89
	v_and_b32_e32 v18, 0xffff0000, v90
	v_and_b32_e32 v21, 0xffff0000, v93
	v_mov_b32_e32 v20, v19
	s_cmp_eq_u32 s1, 7
	v_pk_fma_f32 v[124:125], v[128:129], v[104:105], v[130:131] op_sel_hi:[0,1,0]
	v_pk_fma_f32 v[126:127], v[128:129], v[80:81], v[130:131] op_sel_hi:[0,1,0]
	v_pk_fma_f32 v[22:23], v[128:129], v[22:23], v[130:131] op_sel_hi:[0,1,0]
	v_pk_fma_f32 v[106:107], v[128:129], v[106:107], v[130:131] op_sel_hi:[0,1,0]
	v_pk_fma_f32 v[22:23], v[132:133], v[116:117], v[22:23] op_sel_hi:[0,1,1]
	v_pk_fma_f32 v[116:117], v[132:133], v[114:115], v[126:127] op_sel_hi:[0,1,1]
	v_pk_fma_f32 v[124:125], v[132:133], v[118:119], v[124:125] op_sel_hi:[0,1,1]
	v_pk_fma_f32 v[106:107], v[132:133], v[108:109], v[106:107] op_sel_hi:[0,1,1]
	v_pk_fma_f32 v[22:23], v[134:135], v[80:81], v[22:23] op_sel_hi:[0,1,1]
	v_pk_fma_f32 v[80:81], v[134:135], v[104:105], v[116:117] op_sel_hi:[0,1,1]
	v_pk_fma_f32 v[104:105], v[134:135], v[120:121], v[124:125] op_sel_hi:[0,1,1]
	v_pk_fma_f32 v[106:107], v[134:135], v[110:111], v[106:107] op_sel_hi:[0,1,1]
	v_pk_fma_f32 v[104:105], v[136:137], v[122:123], v[104:105] op_sel_hi:[0,1,1]
	v_pk_fma_f32 v[106:107], v[136:137], v[112:113], v[106:107] op_sel_hi:[0,1,1]
	v_mul_f32_e32 v110, 0xbfb8aa3b, v104
	v_mul_f32_e32 v111, 0xbfb8aa3b, v105
	v_pk_fma_f32 v[80:81], v[136:137], v[118:119], v[80:81] op_sel_hi:[0,1,1]
	v_mul_f32_e32 v112, 0xbfb8aa3b, v106
	v_mul_f32_e32 v113, 0xbfb8aa3b, v107
	v_exp_f32_e32 v110, v110
	v_exp_f32_e32 v111, v111
	v_mul_f32_e32 v108, 0xbfb8aa3b, v80
	v_mul_f32_e32 v109, 0xbfb8aa3b, v81
	v_exp_f32_e32 v112, v112
	v_exp_f32_e32 v113, v113
	v_exp_f32_e32 v108, v108
	v_exp_f32_e32 v109, v109
	v_add_f32_e32 v116, 1.0, v110
	v_add_f32_e32 v117, 1.0, v111
	v_pk_fma_f32 v[22:23], v[136:137], v[114:115], v[22:23] op_sel_hi:[0,1,1]
	v_add_f32_e32 v118, 1.0, v112
	v_add_f32_e32 v119, 1.0, v113
	v_rcp_f32_e32 v112, v116
	v_rcp_f32_e32 v113, v117
	v_mul_f32_e32 v27, 0xbfb8aa3b, v22
	v_add_f32_e32 v114, 1.0, v108
	v_add_f32_e32 v115, 1.0, v109
	v_mul_f32_e32 v82, 0xbfb8aa3b, v23
	v_exp_f32_e32 v27, v27
	v_rcp_f32_e32 v110, v114
	v_rcp_f32_e32 v111, v115
	v_rcp_f32_e32 v114, v118
	v_rcp_f32_e32 v115, v119
	v_and_b32_e32 v117, 0xffff0000, v85
	v_and_b32_e32 v116, 0xffff0000, v86
	v_and_b32_e32 v119, 0xffff0000, v83
	v_and_b32_e32 v118, 0xffff0000, v84
	v_exp_f32_e32 v82, v82
	v_pk_fma_f32 v[120:121], v[128:129], v[118:119], v[130:131] op_sel:[1,0,1]
	v_pk_mov_b32 v[118:119], v[118:119], v[116:117] op_sel:[1,0]
	v_pk_mul_f32 v[104:105], v[104:105], v[112:113]
	v_and_b32_e32 v113, 0xffff0000, v87
	v_and_b32_e32 v112, 0xffff0000, v88
	v_pk_fma_f32 v[118:119], v[132:133], v[118:119], v[120:121] op_sel:[1,0,0]
	v_pk_mov_b32 v[122:123], v[116:117], v[112:113] op_sel:[1,0]
	v_pk_fma_f32 v[118:119], v[134:135], v[116:117], v[118:119] op_sel:[1,0,0]
	v_add_f32_e32 v27, 1.0, v27
	v_pk_fma_f32 v[118:119], v[136:137], v[122:123], v[118:119] op_sel:[1,0,0]
	v_add_f32_e32 v82, 1.0, v82
	v_rcp_f32_e32 v108, v27
	v_mul_f32_e32 v27, 0xbfb8aa3b, v118
	v_rcp_f32_e32 v109, v82
	v_exp_f32_e32 v27, v27
	v_mul_f32_e32 v82, 0xbfb8aa3b, v119
	v_exp_f32_e32 v82, v82
	v_pk_fma_f32 v[116:117], v[128:129], v[116:117], v[130:131] op_sel:[1,0,1]
	v_pk_mul_f32 v[106:107], v[106:107], v[114:115]
	v_pk_fma_f32 v[116:117], v[132:133], v[122:123], v[116:117] op_sel:[1,0,0]
	v_pk_fma_f32 v[114:115], v[128:129], v[112:113], v[130:131] op_sel:[1,0,1]
	v_pk_mov_b32 v[124:125], v[112:113], v[18:19] op_sel:[1,0]
	v_pk_fma_f32 v[112:113], v[134:135], v[112:113], v[116:117] op_sel:[1,0,0]
	v_add_f32_e32 v27, 1.0, v27
	v_pk_fma_f32 v[112:113], v[136:137], v[124:125], v[112:113] op_sel:[1,0,0]
	v_rcp_f32_e32 v120, v27
	v_add_f32_e32 v27, 1.0, v82
	v_mul_f32_e32 v82, 0xbfb8aa3b, v112
	v_exp_f32_e32 v82, v82
	v_mul_f32_e32 v116, 0xbfb8aa3b, v113
	v_exp_f32_e32 v117, v116
	v_pk_fma_f32 v[114:115], v[132:133], v[124:125], v[114:115] op_sel:[1,0,0]
	v_pk_fma_f32 v[8:9], v[128:129], v[18:19], v[130:131] op_sel:[1,0,1]
	v_pk_mul_f32 v[22:23], v[22:23], v[108:109]
	v_and_b32_e32 v109, 0xffff0000, v92
	v_mov_b32_e32 v108, v21
	v_pk_fma_f32 v[114:115], v[134:135], v[18:19], v[114:115] op_sel:[1,0,0]
	v_pk_fma_f32 v[8:9], v[132:133], v[20:21], v[8:9] op_sel:[1,0,0]
	v_pk_mul_f32 v[80:81], v[80:81], v[110:111]
	v_and_b32_e32 v111, 0xffff0000, v99
	v_mov_b32_e32 v110, v109
	v_pk_fma_f32 v[114:115], v[136:137], v[20:21], v[114:115] op_sel:[1,0,0]
	v_pk_fma_f32 v[8:9], v[134:135], v[108:109], v[8:9] op_sel:[1,0,0]
	v_rcp_f32_e32 v121, v27
	v_add_f32_e32 v27, 1.0, v82
	v_mul_f32_e32 v82, 0xbfb8aa3b, v114
	v_pk_fma_f32 v[8:9], v[136:137], v[110:111], v[8:9] op_sel:[1,0,0]
	v_rcp_f32_e32 v116, v27
	v_add_f32_e32 v27, 1.0, v117
	v_exp_f32_e32 v82, v82
	v_mul_f32_e32 v117, 0xbfb8aa3b, v115
	v_mul_f32_e32 v10, 0xbfb8aa3b, v8
	v_mul_f32_e32 v11, 0xbfb8aa3b, v9
	v_exp_f32_e32 v123, v117
	v_exp_f32_e32 v10, v10
	v_exp_f32_e32 v11, v11
	v_rcp_f32_e32 v117, v27
	v_add_f32_e32 v27, 1.0, v82
	v_rcp_f32_e32 v122, v27
	v_add_f32_e32 v27, 1.0, v123
	v_add_f32_e32 v10, 1.0, v10
	v_add_f32_e32 v11, 1.0, v11
	v_rcp_f32_e32 v123, v27
	v_rcp_f32_e32 v10, v10
	v_rcp_f32_e32 v11, v11
	v_pk_mul_f32 v[12:13], v[118:119], v[120:121]
	v_pk_mul_f32 v[14:15], v[112:113], v[116:117]
	v_pk_mul_f32 v[16:17], v[114:115], v[122:123]
	v_pk_mul_f32 v[18:19], v[8:9], v[10:11]
	v_cvt_pk_bf16_f32 v8, v22, v23
	v_cvt_pk_bf16_f32 v9, v80, v81
	v_cvt_pk_bf16_f32 v10, v104, v105
	v_cvt_pk_bf16_f32 v11, v106, v107
	ds_write_b128 v96, v[8:11] offset:43008
	v_cvt_pk_bf16_f32 v8, v12, v13
	v_cvt_pk_bf16_f32 v9, v14, v15
	v_cvt_pk_bf16_f32 v10, v16, v17
	v_cvt_pk_bf16_f32 v11, v18, v19
	ds_write_b128 v96, v[8:11] offset:43280
	ds_write_b128 v100, v[4:7] offset:60416
	ds_write_b128 v100, v[0:3] offset:60432
	s_waitcnt lgkmcnt(0)
	s_barrier
	s_cbranch_scc1 .LBB0_394
	s_add_i32 s7, s1, s2
	s_lshl_b32 s4, s7, 7
	s_mov_b32 s5, s31
	v_lshl_add_u64 v[0:1], v[58:59], 0, s[4:5]
	v_mov_b32_e32 v83, 0
	v_mov_b32_e32 v84, 0
	s_and_saveexec_b64 s[4:5], s[40:41]
	s_cbranch_execz .LBB0_375
	v_lshl_add_u64 v[2:3], v[0:1], 0, v[28:29]
	global_load_dword v84, v[2:3], off

.LBB0_393:
	s_or_b64 exec, exec, s[4:5]
	s_add_i32 s4, s7, s0
	s_ashr_i32 s5, s4, 31
	s_lshl_b32 s8, s7, 6
	s_lshl_b64 s[4:5], s[4:5], 14
	v_lshl_add_u64 v[4:5], v[60:61], 0, s[4:5]
	s_lshl_b32 s4, s8, 1
	s_mov_b32 s5, s31
	v_lshl_add_u64 v[8:9], v[62:63], 0, s[4:5]
	global_load_dwordx4 v[0:3], v[4:5], off offset:16
	s_nop 0
	global_load_dwordx4 v[4:7], v[4:5], off
	s_nop 0
	global_load_dwordx2 v[64:65], v[8:9], off
	global_load_dwordx2 v[66:67], v[8:9], off offset:32
	global_load_dwordx2 v[68:69], v[8:9], off offset:64
	global_load_dwordx2 v[70:71], v[8:9], off offset:96
	s_add_i32 s4, s46, 1
	s_lshl_b32 s4, s4, 8
	s_mov_b32 s5, 0
	v_lshl_add_u64 v[138:139], v[54:55], 0, s[4:5]
	v_lshl_add_u64 v[140:141], v[56:57], 0, s[4:5]
	global_load_dwordx2 v[128:129], v[138:139], off
	global_load_dwordx2 v[130:131], v[140:141], off
	s_mov_b64 s[4:5], 0x6000
	v_lshl_add_u64 v[140:141], v[138:139], 0, s[4:5]
	global_load_dwordx2 v[132:133], v[140:141], off
	s_mov_b64 s[4:5], 0xc000
	v_lshl_add_u64 v[140:141], v[138:139], 0, s[4:5]
	global_load_dwordx2 v[134:135], v[140:141], off
	s_mov_b64 s[4:5], 0x12000
	v_lshl_add_u64 v[140:141], v[138:139], 0, s[4:5]
	global_load_dwordx2 v[136:137], v[140:141], off
.LBB0_394:
	s_mov_b32 s47, s31
	s_lshl_b64 s[4:5], s[46:47], 2
	s_add_u32 s4, s84, s4
	s_addc_u32 s5, s85, s5
	global_load_dword v142, v173, s[4:5]
	v_mov_b32_e32 v8, v173
	v_mov_b32_e32 v12, v173
	v_mov_b32_e32 v16, v173
	v_mov_b32_e32 v20, v173
	v_add_u32_e32 v27, v38, v41
	ds_read_b128 v[104:107], v40 offset:8192
	ds_read_b128 v[108:111], v27 offset:60416
	ds_read_b128 v[112:115], v27 offset:64768
	ds_read_b128 v[116:119], v97 offset:60416
	ds_read_b128 v[120:123], v98 offset:60416
	v_mov_b32_e32 v9, v8
	v_mov_b32_e32 v10, v8
	v_mov_b32_e32 v11, v8
	v_mov_b32_e32 v13, v12
	v_mov_b32_e32 v14, v12
	v_mov_b32_e32 v15, v12
	v_mov_b32_e32 v17, v16
	v_mov_b32_e32 v18, v16
	v_mov_b32_e32 v19, v16
	v_mov_b32_e32 v21, v20
	v_mov_b32_e32 v22, v20
	v_mov_b32_e32 v23, v20
	s_waitcnt lgkmcnt(3)
	v_mfma_f32_16x16x32_bf16 v[8:11], v[108:111], v[104:107], v[8:11]
	s_waitcnt lgkmcnt(2)
	v_mfma_f32_16x16x32_bf16 v[12:15], v[112:115], v[104:107], v[12:15]
	s_waitcnt lgkmcnt(1)
	v_mfma_f32_16x16x32_bf16 v[16:19], v[116:119], v[104:107], v[16:19]
	s_waitcnt lgkmcnt(0)
	v_mfma_f32_16x16x32_bf16 v[20:23], v[120:123], v[104:107], v[20:23]
	ds_read_b128 v[104:107], v40 offset:8256
	ds_read_b128 v[108:111], v27 offset:60480
	ds_read_b128 v[112:115], v27 offset:64832
	ds_read_b128 v[116:119], v97 offset:60480
	ds_read_b128 v[120:123], v98 offset:60480
	s_waitcnt lgkmcnt(3)
	v_mfma_f32_16x16x32_bf16 v[8:11], v[108:111], v[104:107], v[8:11]
	s_waitcnt lgkmcnt(2)
	v_mfma_f32_16x16x32_bf16 v[12:15], v[112:115], v[104:107], v[12:15]
	s_waitcnt lgkmcnt(1)
	v_mfma_f32_16x16x32_bf16 v[16:19], v[116:119], v[104:107], v[16:19]
	s_waitcnt lgkmcnt(0)
	v_mfma_f32_16x16x32_bf16 v[20:23], v[120:123], v[104:107], v[20:23]
	ds_read_b128 v[104:107], v40 offset:8320
	ds_read_b128 v[108:111], v27 offset:60544
	ds_read_b128 v[112:115], v27 offset:64896
	ds_read_b128 v[116:119], v97 offset:60544
	ds_read_b128 v[120:123], v98 offset:60544
	s_waitcnt lgkmcnt(3)
	v_mfma_f32_16x16x32_bf16 v[8:11], v[108:111], v[104:107], v[8:11]
	s_waitcnt lgkmcnt(2)
	v_mfma_f32_16x16x32_bf16 v[12:15], v[112:115], v[104:107], v[12:15]
	s_waitcnt lgkmcnt(1)
	v_mfma_f32_16x16x32_bf16 v[16:19], v[116:119], v[104:107], v[16:19]
	s_waitcnt lgkmcnt(0)
	v_mfma_f32_16x16x32_bf16 v[20:23], v[120:123], v[104:107], v[20:23]
	ds_read_b128 v[104:107], v40 offset:8384
	ds_read_b128 v[108:111], v27 offset:60608
	ds_read_b128 v[112:115], v27 offset:64960
	ds_read_b128 v[116:119], v97 offset:60608
	ds_read_b128 v[120:123], v98 offset:60608
	s_waitcnt lgkmcnt(3)
	v_mfma_f32_16x16x32_bf16 v[8:11], v[108:111], v[104:107], v[8:11]
	s_andn2_b64 vcc, exec, s[44:45]
	v_mov_b32_e32 v82, v26
	s_mov_b32 s4, s6
	s_waitcnt lgkmcnt(1)
	v_mfma_f32_16x16x32_bf16 v[108:111], v[116:119], v[104:107], v[16:19]
	s_nop 2
	v_lshl_add_u32 v16, s1, 9, v91
	ds_read_b32 v27, v16
	v_mfma_f32_16x16x32_bf16 v[12:15], v[112:115], v[104:107], v[12:15]
	s_waitcnt lgkmcnt(0)
	v_mul_f32_e32 v16, 0x3fb8aa3b, v27
	v_mfma_f32_16x16x32_bf16 v[104:107], v[120:123], v[104:107], v[20:23]
	v_exp_f32_e32 v80, v16
	s_nop 3
	v_pk_mul_f32 v[18:19], v[14:15], v[80:81] op_sel_hi:[1,0]
	v_pk_mul_f32 v[22:23], v[10:11], v[80:81] op_sel_hi:[1,0]
	v_pk_mul_f32 v[20:21], v[8:9], v[80:81] op_sel_hi:[1,0]
	v_pk_mul_f32 v[16:17], v[12:13], v[80:81] op_sel_hi:[1,0]
	v_pk_mul_f32 v[14:15], v[110:111], v[80:81] op_sel_hi:[1,0]
	v_pk_mul_f32 v[12:13], v[108:109], v[80:81] op_sel_hi:[1,0]
	v_pk_mul_f32 v[10:11], v[106:107], v[80:81] op_sel_hi:[1,0]
	v_pk_mul_f32 v[8:9], v[104:105], v[80:81] op_sel_hi:[1,0]
	v_mov_b32_e32 v80, v102
	v_mov_b32_e32 v81, v95
	v_mov_b32_e32 v104, v94
	s_cbranch_vccnz .LBB0_396

.LBB0_396:
	v_lshlrev_b32_e32 v104, 16, v78
	v_mul_f32_e32 v27, 0xbfb8aa3b, v104
	v_exp_f32_e32 v27, v27
	v_and_b32_e32 v105, 0xffff0000, v78
	s_lshl_b32 s30, s30, 1
	v_lshl_add_u64 v[80:81], v[62:63], 0, s[30:31]
	v_add_f32_e32 v27, 1.0, v27
	v_rcp_f32_e32 v106, v27
	ds_read_u16 v27, v101 offset:43008
	ds_read_u16 v78, v101 offset:43280
	s_add_i32 s1, s1, 1
	v_add_u32_e32 v95, 0x200, v95
	s_cmp_eq_u32 s1, 8
	s_waitcnt lgkmcnt(1)
	v_lshlrev_b32_e32 v108, 16, v27
	v_mul_f32_e32 v27, 0xbfb8aa3b, v105
	v_exp_f32_e32 v27, v27
	s_waitcnt lgkmcnt(0)
	v_lshlrev_b32_e32 v109, 16, v78
	v_lshlrev_b32_e32 v78, 16, v79
	v_and_b32_e32 v79, 0xffff0000, v79
	v_add_f32_e32 v27, 1.0, v27
	v_rcp_f32_e32 v107, v27
	s_waitcnt vmcnt(0)
	v_pk_fma_f32 v[20:21], v[142:143], v[108:109], v[20:21] op_sel_hi:[0,1,1]
	v_pk_mul_f32 v[104:105], v[106:107], v[104:105]
	s_nop 0
	v_pk_mul_f32 v[20:21], v[104:105], v[20:21]
	s_nop 0
	v_pk_mul_f32 v[104:105], v[20:21], v[20:21]
	v_cvt_pk_bf16_f32 v20, v20, v21
	v_add_f32_e32 v27, v103, v104
	v_mul_f32_e32 v103, 0xbfb8aa3b, v78
	v_exp_f32_e32 v103, v103
	v_add_f32_e32 v27, v27, v105
	v_add_f32_e32 v103, 1.0, v103
	v_rcp_f32_e32 v104, v103
	ds_read_u16 v103, v101 offset:43552
	ds_read_u16 v105, v101 offset:43824
	s_waitcnt lgkmcnt(1)
	v_lshlrev_b32_e32 v106, 16, v103
	v_mul_f32_e32 v103, 0xbfb8aa3b, v79
	v_exp_f32_e32 v103, v103
	s_waitcnt lgkmcnt(0)
	v_lshlrev_b32_e32 v107, 16, v105
	v_pk_fma_f32 v[22:23], v[142:143], v[106:107], v[22:23] op_sel_hi:[0,1,1]
	v_add_f32_e32 v103, 1.0, v103
	v_rcp_f32_e32 v105, v103
	s_nop 0
	v_pk_mul_f32 v[78:79], v[104:105], v[78:79]
	s_nop 0
	v_pk_mul_f32 v[22:23], v[78:79], v[22:23]
	s_nop 0
	v_cvt_pk_bf16_f32 v21, v22, v23
	global_store_dwordx2 v[80:81], v[20:21], off
	v_pk_mul_f32 v[78:79], v[22:23], v[22:23]
	v_lshlrev_b32_e32 v20, 16, v76
	v_and_b32_e32 v21, 0xffff0000, v76
	ds_read_u16 v23, v101 offset:47360
	ds_read_u16 v76, v101 offset:47632
	v_add_f32_e32 v27, v27, v78
	v_mul_f32_e32 v22, 0xbfb8aa3b, v20
	v_exp_f32_e32 v22, v22
	s_waitcnt lgkmcnt(1)
	v_lshlrev_b32_e32 v78, 16, v23
	v_mul_f32_e32 v23, 0xbfb8aa3b, v21
	v_exp_f32_e32 v23, v23
	v_add_f32_e32 v22, 1.0, v22
	v_rcp_f32_e32 v22, v22
	v_add_f32_e32 v27, v27, v79
	v_add_f32_e32 v23, 1.0, v23
	v_rcp_f32_e32 v23, v23
	s_waitcnt lgkmcnt(0)
	v_lshlrev_b32_e32 v79, 16, v76
	v_pk_fma_f32 v[16:17], v[142:143], v[78:79], v[16:17] op_sel_hi:[0,1,1]
	v_pk_mul_f32 v[20:21], v[22:23], v[20:21]
	ds_read_u16 v23, v101 offset:47904
	ds_read_u16 v76, v101 offset:48176
	v_pk_mul_f32 v[16:17], v[20:21], v[16:17]
	s_nop 0
	v_pk_mul_f32 v[20:21], v[16:17], v[16:17]
	v_cvt_pk_bf16_f32 v16, v16, v17
	v_add_f32_e32 v20, v27, v20
	v_add_f32_e32 v27, v20, v21
	v_lshlrev_b32_e32 v20, 16, v77
	v_and_b32_e32 v21, 0xffff0000, v77
	v_mul_f32_e32 v22, 0xbfb8aa3b, v20
	s_waitcnt lgkmcnt(0)
	v_lshlrev_b32_e32 v77, 16, v76
	v_lshlrev_b32_e32 v76, 16, v23
	v_mul_f32_e32 v23, 0xbfb8aa3b, v21
	v_exp_f32_e32 v22, v22
	v_exp_f32_e32 v23, v23
	v_pk_fma_f32 v[18:19], v[142:143], v[76:77], v[18:19] op_sel_hi:[0,1,1]
	v_add_f32_e32 v22, 1.0, v22
	v_add_f32_e32 v23, 1.0, v23
	v_rcp_f32_e32 v22, v22
	v_rcp_f32_e32 v23, v23
	s_nop 0
	v_pk_mul_f32 v[20:21], v[22:23], v[20:21]
	s_nop 0
	v_pk_mul_f32 v[18:19], v[20:21], v[18:19]
	s_nop 0
	v_pk_mul_f32 v[20:21], v[18:19], v[18:19]
	v_cvt_pk_bf16_f32 v17, v18, v19
	v_add_f32_e32 v20, v27, v20
	global_store_dwordx2 v[80:81], v[16:17], off offset:32
	v_add_f32_e32 v22, v20, v21
	ds_read_u16 v19, v101 offset:51712
	ds_read_u16 v20, v101 offset:51984
	v_lshlrev_b32_e32 v16, 16, v74
	v_and_b32_e32 v17, 0xffff0000, v74
	v_mul_f32_e32 v18, 0xbfb8aa3b, v16
	v_exp_f32_e32 v18, v18
	s_waitcnt lgkmcnt(0)
	v_lshlrev_b32_e32 v21, 16, v20
	v_lshlrev_b32_e32 v20, 16, v19
	v_mul_f32_e32 v19, 0xbfb8aa3b, v17
	v_exp_f32_e32 v19, v19
	v_add_f32_e32 v18, 1.0, v18
	v_rcp_f32_e32 v18, v18
	v_pk_fma_f32 v[12:13], v[142:143], v[20:21], v[12:13] op_sel_hi:[0,1,1]
	v_add_f32_e32 v19, 1.0, v19
	v_rcp_f32_e32 v19, v19
	s_nop 0
	v_pk_mul_f32 v[16:17], v[18:19], v[16:17]
	ds_read_u16 v19, v101 offset:52256
	ds_read_u16 v20, v101 offset:52528
	v_pk_mul_f32 v[12:13], v[16:17], v[12:13]
	s_waitcnt lgkmcnt(0)
	v_lshlrev_b32_e32 v21, 16, v20
	v_pk_mul_f32 v[16:17], v[12:13], v[12:13]
	v_lshlrev_b32_e32 v20, 16, v19
	v_add_f32_e32 v16, v22, v16
	v_add_f32_e32 v22, v16, v17
	v_lshlrev_b32_e32 v16, 16, v75
	v_and_b32_e32 v17, 0xffff0000, v75
	v_mul_f32_e32 v18, 0xbfb8aa3b, v16
	v_mul_f32_e32 v19, 0xbfb8aa3b, v17
	v_exp_f32_e32 v18, v18
	v_exp_f32_e32 v19, v19
	v_pk_fma_f32 v[14:15], v[142:143], v[20:21], v[14:15] op_sel_hi:[0,1,1]
	v_cvt_pk_bf16_f32 v12, v12, v13
	v_add_f32_e32 v18, 1.0, v18
	v_add_f32_e32 v19, 1.0, v19
	v_rcp_f32_e32 v18, v18
	v_rcp_f32_e32 v19, v19
	s_nop 0
	v_pk_mul_f32 v[16:17], v[18:19], v[16:17]
	s_nop 0
	v_pk_mul_f32 v[14:15], v[16:17], v[14:15]
	s_nop 0
	v_pk_mul_f32 v[16:17], v[14:15], v[14:15]
	v_cvt_pk_bf16_f32 v13, v14, v15
	v_add_f32_e32 v16, v22, v16
	global_store_dwordx2 v[80:81], v[12:13], off offset:64
	v_add_f32_e32 v18, v16, v17
	ds_read_u16 v15, v101 offset:56064
	ds_read_u16 v16, v101 offset:56336
	v_lshlrev_b32_e32 v12, 16, v72
	v_and_b32_e32 v13, 0xffff0000, v72
	v_mul_f32_e32 v14, 0xbfb8aa3b, v12
	v_exp_f32_e32 v14, v14
	s_waitcnt lgkmcnt(0)
	v_lshlrev_b32_e32 v17, 16, v16
	v_lshlrev_b32_e32 v16, 16, v15
	v_mul_f32_e32 v15, 0xbfb8aa3b, v13
	v_exp_f32_e32 v15, v15
	v_add_f32_e32 v14, 1.0, v14
	v_rcp_f32_e32 v14, v14
	v_pk_fma_f32 v[8:9], v[142:143], v[16:17], v[8:9] op_sel_hi:[0,1,1]
	v_add_f32_e32 v15, 1.0, v15
	v_rcp_f32_e32 v15, v15
	s_nop 0
	v_pk_mul_f32 v[12:13], v[14:15], v[12:13]
	ds_read_u16 v15, v101 offset:56608
	ds_read_u16 v16, v101 offset:56880
	v_pk_mul_f32 v[8:9], v[12:13], v[8:9]
	s_waitcnt lgkmcnt(0)
	v_lshlrev_b32_e32 v17, 16, v16
	v_pk_mul_f32 v[12:13], v[8:9], v[8:9]
	v_lshlrev_b32_e32 v16, 16, v15
	v_add_f32_e32 v12, v18, v12
	v_add_f32_e32 v18, v12, v13
	v_lshlrev_b32_e32 v12, 16, v73
	v_and_b32_e32 v13, 0xffff0000, v73
	v_mul_f32_e32 v14, 0xbfb8aa3b, v12
	v_mul_f32_e32 v15, 0xbfb8aa3b, v13
	v_exp_f32_e32 v14, v14
	v_exp_f32_e32 v15, v15
	v_pk_fma_f32 v[10:11], v[142:143], v[16:17], v[10:11] op_sel_hi:[0,1,1]
	v_cvt_pk_bf16_f32 v8, v8, v9
	v_add_f32_e32 v14, 1.0, v14
	v_add_f32_e32 v15, 1.0, v15
	v_rcp_f32_e32 v14, v14
	v_rcp_f32_e32 v15, v15
	s_nop 0
	v_pk_mul_f32 v[12:13], v[14:15], v[12:13]
	s_nop 0
	v_pk_mul_f32 v[10:11], v[12:13], v[10:11]
	s_nop 0
	v_pk_mul_f32 v[12:13], v[10:11], v[10:11]
	v_cvt_pk_bf16_f32 v9, v10, v11
	v_add_f32_e32 v12, v18, v12
	v_add_f32_e32 v103, v12, v13
	global_store_dwordx2 v[80:81], v[8:9], off offset:96
	s_barrier
	s_cbranch_scc1 .LBB0_400
	v_mov_b64_e32 v[72:73], v[70:71]
	v_mov_b64_e32 v[74:75], v[68:69]
	v_mov_b64_e32 v[76:77], v[66:67]
	v_mov_b64_e32 v[78:79], v[64:65]
	s_branch .LBB0_372
